# claim-ahead also at the attention-phase conversion site (on top of the XCD-split / trimmed-barrier version, 5 idle tiles)
# baseline (speedup 1.0000x reference)
; #define LAS __attribute__((address_space(3)))
; __device__ __forceinline__ unsigned pk2(float lo, float hi) { return f2bf(lo) | (f2bf(hi) << 16); }
; __device__ __forceinline__ void tr_to_lds(LAS unsigned* T, int tid, const f32x4 (&v)[8][2]) {
;     const int c4 = (tid & 15) + 16 * ((tid >> 6) & 1), rp = ((tid >> 4) & 3) + 4 * (tid >> 7);
; #pragma unroll
;     for (int i = 0; i < 8; ++i)
; #pragma unroll
;         for (int j = 0; j < 4; ++j) T[(4 * c4 + j) * 132 + 16 * i + rp] = pk2(v[i][0][j], v[i][1][j]);
; }
; __device__ __forceinline__ void tr_store(const TrJob& jb, const LAS unsigned* T, int tid, int k0, int n0) {
;     const int w = tid >> 6, lane = tid & 63, c = 8 * (w >> 1) + (lane & 7), nb = 64 * (w & 1) + (lane >> 3);
.LBB0_1039:
	v_and_b32_e32 v69, -4, v71
	v_ashrrev_i32_e32 v71, 4, v2
	v_bfe_u32 v68, v2, 4, 2
	s_cmp_lg_u32 s16, 0
	v_bfi_b32 v71, -8, v71, v2
	v_lshrrev_b32_e32 v2, 3, v2
	s_cselect_b64 s[4:5], -1, 0
	v_lshlrev_b32_e32 v68, 2, v68
	v_lshlrev_b32_e32 v69, 2, v69
	v_and_or_b32 v79, v2, 7, v70
	s_cmp_lg_u64 s[4:5], 0
	v_readlane_b32 s4, v254, 37
	v_add3_u32 v68, 0, v68, v69
	v_mul_u32_u24_e32 v69, 0x210, v77
	v_lshl_add_u32 v2, v71, 4, 0
	v_mul_u32_u24_e32 v70, 0x210, v79
	s_subb_u32 s21, s4, 0
	v_lshlrev_b32_e32 v80, 3, v71
	v_or_b32_e32 v81, 8, v79
	v_or_b32_e32 v82, 16, v79
	v_or_b32_e32 v83, 24, v79
	v_or_b32_e32 v84, 32, v79
	v_or_b32_e32 v85, 40, v79
	v_or_b32_e32 v86, 48, v79
	v_or_b32_e32 v87, 56, v79
	v_add_u32_e32 v88, v68, v69
	v_add_u32_e32 v89, v2, v70
	s_mov_b32 s83, 0
	s_branch .LBB0_1041

; #define LAS __attribute__((address_space(3)))
; __device__ __forceinline__ unsigned pk2(float lo, float hi) { return f2bf(lo) | (f2bf(hi) << 16); }
; __device__ __forceinline__ void tr_to_lds(LAS unsigned* T, int tid, const f32x4 (&v)[8][2]) {
;     const int c4 = (tid & 15) + 16 * ((tid >> 6) & 1), rp = ((tid >> 4) & 3) + 4 * (tid >> 7);
; #pragma unroll
;     for (int i = 0; i < 8; ++i)
; #pragma unroll
;         for (int j = 0; j < 4; ++j) T[(4 * c4 + j) * 132 + 16 * i + rp] = pk2(v[i][0][j], v[i][1][j]);
; __device__ __forceinline__ unsigned conv_claim(unsigned* ctr, volatile LAS unsigned* slot, int limit, int extra, unsigned known, bool peek) {
;     if (peek) known = __hip_atomic_load(ctr, __ATOMIC_RELAXED, __HIP_MEMORY_SCOPE_AGENT);
;     const bool need = (int)known < limit, opt = !need && extra > 0 && (int)known < TL_ALL;
;     unsigned T = 0xffffffffu;
;     if (need || opt) { T = __hip_atomic_fetch_add(ctr, 1u, __ATOMIC_RELAXED, __HIP_MEMORY_SCOPE_AGENT); known = T + 1u; if ((int)T >= TL_ALL) T = 0xffffffffu; }
;     slot[0] = T; slot[1] = need ? 0u : 1u;
.Lgm__1041_15:
	v_bfe_u32 v73, v64, 16, 1
	v_lshrrev_b32_e32 v72, 16, v72
	v_add3_u32 v73, v64, v73, s81
	v_and_or_b32 v72, v73, s82, v72
	ds_write2_b32 v88, v2, v72 offset0:96 offset1:112
	v_bfe_u32 v2, v61, 16, 1
	v_add3_u32 v2, v61, v2, s81
	v_bfe_u32 v72, v65, 16, 1
	v_lshrrev_b32_e32 v2, 16, v2
	v_add3_u32 v72, v65, v72, s81
	v_and_or_b32 v2, v72, s82, v2
	ds_write2_b32 v88, v69, v2 offset0:228 offset1:244
	v_bfe_u32 v2, v62, 16, 1
	v_add3_u32 v2, v62, v2, s81
	v_bfe_u32 v69, v66, 16, 1
	v_lshrrev_b32_e32 v2, 16, v2
	v_add3_u32 v69, v66, v69, s81
	v_and_or_b32 v2, v69, s82, v2
	ds_write2_b32 v68, v70, v2 offset0:104 offset1:120
	v_bfe_u32 v2, v63, 16, 1
	v_add3_u32 v2, v63, v2, s81
	v_bfe_u32 v69, v67, 16, 1
	v_lshrrev_b32_e32 v2, 16, v2
	v_add3_u32 v69, v67, v69, s81
	s_mov_b32 s24, s15
	s_mov_b32 s28, s14
	s_mov_b64 s[6:7], s[0:1]
	s_mov_b32 s22, s19
	s_mov_b32 s25, s34
	s_mov_b32 s23, s20
	v_and_or_b32 v2, v69, s82, v2
	ds_write2_b32 v68, v71, v2 offset0:236 offset1:252
	s_and_saveexec_b64 s[4:5], s[2:3]
	s_cbranch_execz .LBB0_1047
	s_cmp_lg_u32 s83, 0
	s_cbranch_scc0 .Lca1041_orig
	s_mov_b32 s83, 0
	s_mov_b64 s[8:9], exec
	s_cmp_lg_u32 s65, 0
	s_cselect_b64 vcc, exec, 0
	v_mov_b32_e32 v2, 0
	s_waitcnt vmcnt(0)
	v_mov_b32_e32 v68, v142
	s_branch .Lca1041_join

; #define LAS __attribute__((address_space(3)))
; __device__ __forceinline__ void tr_load(const TrJob& jb, int tile, int tid, f32x4 (&v)[8][2], int& k0, int& n0) {
;     ...
;     const float* wp = jb.W + (size_t)(k0 + 2 * rp) * jb.N + col;
; #pragma unroll
;     for (int i = 0; i < 8; ++i) { v[i][0] = *(const f32x4*)(wp + (size_t)(32 * i) * jb.N); v[i][1] = *(const f32x4*)(wp + (size_t)(32 * i + 1) * jb.N); }
;     if (jb.gain) {
; #pragma unroll
;         for (int i = 0; i < 8; ++i) { const float ga = jb.gain[k0 + 32 * i + 2 * rp], gb = jb.gain[k0 + 32 * i + 2 * rp + 1]; v[i][0] = v[i][0] * ga; v[i][1] = v[i][1] * gb; } }
; }
; __device__ __forceinline__ void tr_to_lds(LAS unsigned* T, int tid, const f32x4 (&v)[8][2]) {
;     const int c4 = (tid & 15) + 16 * ((tid >> 6) & 1), rp = ((tid >> 4) & 3) + 4 * (tid >> 7);
; #pragma unroll
;     for (int i = 0; i < 8; ++i)
; #pragma unroll
;         for (int j = 0; j < 4; ++j) T[(4 * c4 + j) * 132 + 16 * i + rp] = pk2(v[i][0][j], v[i][1][j]);
; }
; __device__ __forceinline__ void tr_store(const TrJob& jb, const LAS unsigned* T, int tid, int k0, int n0) {
;     const int w = tid >> 6, lane = tid & 63, c = 8 * (w >> 1) + (lane & 7), nb = 64 * (w & 1) + (lane >> 3);
; #pragma unroll
;     for (int j = 0; j < 8; ++j) { const int n = nb + 8 * j; const v4u o = *(const LAS v4u*)(T + n * 132 + 4 * c);
;         if (n0 + n < jb.N) {
;             if (jb.map == 2 && n0 + n >= GATE_SRC0) {
;                 typedef unsigned v2u_ __attribute__((ext_vector_type(2))); v2u_ q;
;                 q.x = pg8::cvt_pk4_fp8(bflo(o.x) * 256.f, bfhi(o.x) * 256.f, bflo(o.y) * 256.f, bfhi(o.y) * 256.f); q.y = pg8::cvt_pk4_fp8(bflo(o.z) * 256.f, bfhi(o.z) * 256.f, bflo(o.w) * 256.f, bfhi(o.w) * 256.f);
;                 *(v2u_*)((unsigned char*)jb.WT + WIN8_OFF + pg8::blk8_off(n0 + n - GATE_SRC0, k0 + 8 * c, jb.K)) = q; }
; __device__ __forceinline__ unsigned conv_claim(unsigned* ctr, volatile LAS unsigned* slot, int limit, int extra, unsigned known, bool peek) {
;     if (peek) known = __hip_atomic_load(ctr, __ATOMIC_RELAXED, __HIP_MEMORY_SCOPE_AGENT);
;     const bool need = (int)known < limit, opt = !need && extra > 0 && (int)known < TL_ALL;
;     unsigned T = 0xffffffffu;
;     if (need || opt) { T = __hip_atomic_fetch_add(ctr, 1u, __ATOMIC_RELAXED, __HIP_MEMORY_SCOPE_AGENT); known = T + 1u; if ((int)T >= TL_ALL) T = 0xffffffffu; }
.Lgf__1041_22908:
	s_mov_b32 s83, 0
	s_and_saveexec_b64 s[86:87], s[2:3]
	s_cbranch_execz .Lca1041_done
	v_readfirstlane_b32 s27, v76
	s_cmp_lg_u32 s26, 0
	s_cselect_b32 s38, 1, 0
	s_sub_i32 s38, s21, s38
	s_cmp_lt_i32 s27, s18
	s_cselect_b32 s65, 1, 0
	s_cmp_gt_i32 s38, 0
	s_cselect_b32 s38, 1, 0
	s_cmpk_lt_i32 s27, 0x2fa0
	s_cselect_b32 s67, 1, 0
	s_and_b32 s38, s38, s67
	s_or_b32 s38, s38, s65
	s_cmp_lg_u32 s38, 0
	s_cbranch_scc0 .Lca1041_done
	v_mov_b32_e32 v143, 1
	v_readlane_b32 s98, v252, 39
	v_readlane_b32 s99, v252, 40
	s_mov_b32 s83, 1
	s_nop 4
	global_atomic_add v142, v3, v143, s[98:99] sc0
.Lca1041_done:
	s_or_b64 exec, exec, s[86:87]
	global_load_dwordx4 v[4:7], v[4:5], off sc1 nt
	s_nop 0
	global_load_dwordx4 v[8:11], v[12:13], off sc1 nt
	v_lshl_add_u64 v[12:13], v[12:13], 0, s[12:13]
	v_lshl_add_u64 v[20:21], v[12:13], 0, s[10:11]
	global_load_dwordx4 v[12:15], v[12:13], off sc1 nt
	s_nop 0
	global_load_dwordx4 v[16:19], v[20:21], off sc1 nt
	v_lshl_add_u64 v[20:21], v[20:21], 0, s[12:13]
	v_lshl_add_u64 v[28:29], v[20:21], 0, s[10:11]
	global_load_dwordx4 v[20:23], v[20:21], off sc1 nt
	s_nop 0
	global_load_dwordx4 v[24:27], v[28:29], off sc1 nt
	v_lshl_add_u64 v[28:29], v[28:29], 0, s[12:13]
	v_lshl_add_u64 v[36:37], v[28:29], 0, s[10:11]
	v_lshl_add_u64 v[40:41], v[36:37], 0, s[12:13]
	v_lshl_add_u64 v[44:45], v[40:41], 0, s[10:11]
	v_lshl_add_u64 v[48:49], v[44:45], 0, s[12:13]
	v_lshl_add_u64 v[52:53], v[48:49], 0, s[10:11]
	v_lshl_add_u64 v[56:57], v[52:53], 0, s[12:13]
	v_lshl_add_u64 v[60:61], v[56:57], 0, s[10:11]
	v_lshl_add_u64 v[64:65], v[60:61], 0, s[12:13]
	global_load_dwordx4 v[28:31], v[28:29], off sc1 nt
	s_nop 0
	global_load_dwordx4 v[32:35], v[36:37], off sc1 nt
	s_cmp_eq_u64 s[8:9], 0
	global_load_dwordx4 v[36:39], v[40:41], off sc1 nt
	s_nop 0
	global_load_dwordx4 v[40:43], v[44:45], off sc1 nt
	s_nop 0
	global_load_dwordx4 v[44:47], v[48:49], off sc1 nt
	s_nop 0
	global_load_dwordx4 v[48:51], v[52:53], off sc1 nt
	s_nop 0
	global_load_dwordx4 v[52:55], v[56:57], off sc1 nt
	s_nop 0
	global_load_dwordx4 v[56:59], v[60:61], off sc1 nt
	s_nop 0
	global_load_dwordx4 v[60:63], v[64:65], off sc1 nt
	v_lshl_add_u64 v[64:65], v[64:65], 0, s[10:11]
	global_load_dwordx4 v[64:67], v[64:65], off sc1 nt
.LBB0_1081:
	v_add_u32_e32 v2, s28, v80
	v_ashrrev_i32_e32 v72, 6, v2
	v_ashrrev_i32_e32 v74, 7, v2
	v_add_u32_e32 v91, s24, v79
	v_ashrrev_i32_e32 v73, 31, v72
	v_and_b32_e32 v90, 63, v2
	v_ashrrev_i32_e32 v75, 31, v74
	v_and_b32_e32 v2, 0x7f, v2
	v_cmp_gt_i32_e32 vcc, s25, v91
	s_and_saveexec_b64 s[8:9], vcc
	s_cbranch_execz .LBB0_1094
	ds_read_b128 v[68:71], v89
	s_cmp_lg_u32 s23, 2
	s_movk_i32 s12, 0x1110
	s_cselect_b64 s[10:11], -1, 0
	v_cmp_gt_i32_e32 vcc, s12, v91
	s_or_b64 s[10:11], s[10:11], vcc
	s_and_saveexec_b64 s[12:13], s[10:11]
	s_xor_b64 s[10:11], exec, s[12:13]
	s_cbranch_execz .LBB0_1092
	s_cmp_lt_i32 s23, 2
	s_mov_b64 s[12:13], -1
	s_cbranch_scc1 .LBB0_1087
	s_cmp_eq_u32 s23, 2
	v_mov_b32_e32 v92, v91
	s_cbranch_scc0 .LBB0_1086
	s_movk_i32 s12, 0x1110
	v_add_u32_e32 v92, 0xf0, v91
	v_cmp_gt_i32_e32 vcc, s12, v91
	s_nop 1
	v_cndmask_b32_e32 v92, v92, v91, vcc
